# nt hint on the P6 H1 row stores, on top of all row-store exchanges
# baseline (speedup 1.0000x reference)
.LBB0_1592:
	s_or_b64 exec, exec, s[48:49]
	s_waitcnt vmcnt(9)
	v_pk_add_f32 v[92:93], v[92:93], 1.0 op_sel_hi:[1,0]
	s_waitcnt lgkmcnt(0)
	v_pk_mul_f32 v[84:85], v[84:85], v[92:93]
	s_barrier
	v_and_b32_e32 v176, 15, v228
	v_lshrrev_b32_e32 v177, 6, v228
	v_lshrrev_b32_e32 v178, 3, v230
	v_and_b32_e32 v179, 7, v176
	v_xor_b32_e32 v179, v178, v179
	v_mul_u32_u24_e32 v180, 0x2400, v177
	v_add_u32_e32 v180, 0x20000, v180
	v_lshl_add_u32 v144, v176, 9, v180
	v_lshl_add_u32 v144, v179, 4, v144
	v_lshrrev_b32_e32 v181, 5, v230
	v_lshrrev_b32_e32 v182, 5, v236
	v_lshl_add_u32 v181, v181, 2, v182
	v_and_b32_e32 v182, 31, v236
	v_and_b32_e32 v183, 7, v181
	v_xor_b32_e32 v183, v182, v183
	v_lshl_add_u32 v145, v181, 9, v180
	v_lshl_add_u32 v145, v183, 4, v145
	v_add_u32_e32 v183, 2, v181
	v_lshl_add_u32 v146, v183, 9, v180
	v_and_b32_e32 v183, 7, v183
	v_xor_b32_e32 v183, v182, v183
	v_lshl_add_u32 v146, v183, 4, v146
	v_sub_u32_e32 v183, v181, v176
	v_lshlrev_b32_e32 v183, 11, v183
	v_lshlrev_b32_e32 v182, 3, v182
	v_sub_u32_e32 v182, v182, v230
	v_lshl_add_u32 v148, v182, 1, v183
	v_add_u32_e32 v148, 0x800, v148
	v_ashrrev_i32_e32 v149, 31, v148
	ds_read_b32 v92, v232
	s_waitcnt vmcnt(8)
	v_pk_add_f32 v[90:91], v[90:91], 1.0 op_sel_hi:[1,0]
	v_pk_add_f32 v[88:89], v[88:89], 1.0 op_sel_hi:[1,0]
	v_pk_add_f32 v[94:95], v[94:95], 1.0 op_sel_hi:[1,0]
	v_pk_mul_f32 v[82:83], v[82:83], v[90:91]
	v_pk_mul_f32 v[80:81], v[80:81], v[88:89]
	v_lshlrev_b32_e32 v88, 16, v8
	v_and_b32_e32 v89, 0xffff0000, v8
	v_lshlrev_b32_e32 v8, 16, v9
	v_and_b32_e32 v9, 0xffff0000, v9
	v_lshlrev_b32_e32 v90, 16, v10
	v_and_b32_e32 v91, 0xffff0000, v10
	v_lshlrev_b32_e32 v10, 16, v11
	v_and_b32_e32 v11, 0xffff0000, v11
	v_pk_mul_f32 v[86:87], v[86:87], v[94:95]
	s_waitcnt lgkmcnt(0)
	v_pk_mul_f32 v[88:89], v[92:93], v[88:89] op_sel_hi:[0,1]
	v_pk_mul_f32 v[8:9], v[92:93], v[8:9] op_sel_hi:[0,1]
	v_pk_mul_f32 v[90:91], v[92:93], v[90:91] op_sel_hi:[0,1]
	v_pk_mul_f32 v[10:11], v[92:93], v[10:11] op_sel_hi:[0,1]
	s_waitcnt vmcnt(6)
	v_pk_fma_f32 v[8:9], v[82:83], v[8:9], v[78:79]
	v_pk_fma_f32 v[88:89], v[80:81], v[88:89], v[76:77]
	v_pk_fma_f32 v[10:11], v[86:87], v[10:11], v[74:75]
	v_pk_fma_f32 v[90:91], v[84:85], v[90:91], v[72:73]
	v_cvt_pk_bf16_f32 v88, v88, v89
	v_cvt_pk_bf16_f32 v89, v8, v9
	v_lshlrev_b64 v[8:9], 1, v[208:209]
	v_cvt_pk_bf16_f32 v90, v90, v91
	v_cvt_pk_bf16_f32 v91, v10, v11
	v_lshl_add_u64 v[10:11], s[10:11], 0, v[212:213]
	v_lshl_add_u64 v[10:11], v[10:11], 0, v[8:9]
	s_waitcnt vmcnt(2)
	v_pk_add_f32 v[106:107], v[106:107], 1.0 op_sel_hi:[1,0]
	v_pk_add_f32 v[104:105], v[104:105], 1.0 op_sel_hi:[1,0]
	ds_write_b128 v144, v[88:91]
	v_pk_add_f32 v[110:111], v[110:111], 1.0 op_sel_hi:[1,0]
	v_pk_add_f32 v[108:109], v[108:109], 1.0 op_sel_hi:[1,0]
	v_lshlrev_b32_e32 v88, 16, v4
	v_and_b32_e32 v89, 0xffff0000, v4
	v_lshlrev_b32_e32 v4, 16, v5
	v_and_b32_e32 v5, 0xffff0000, v5
	v_pk_mul_f32 v[98:99], v[98:99], v[106:107]
	v_pk_mul_f32 v[96:97], v[96:97], v[104:105]
	v_lshlrev_b32_e32 v90, 16, v6
	v_and_b32_e32 v91, 0xffff0000, v6
	v_lshlrev_b32_e32 v6, 16, v7
	v_and_b32_e32 v7, 0xffff0000, v7
	v_pk_mul_f32 v[88:89], v[92:93], v[88:89] op_sel_hi:[0,1]
	v_pk_mul_f32 v[4:5], v[92:93], v[4:5] op_sel_hi:[0,1]
	v_pk_mul_f32 v[100:101], v[100:101], v[108:109]
	v_pk_mul_f32 v[102:103], v[102:103], v[110:111]
	s_waitcnt vmcnt(0)
	v_pk_fma_f32 v[94:95], v[98:99], v[4:5], v[66:67]
	v_pk_fma_f32 v[4:5], v[96:97], v[88:89], v[64:65]
	v_pk_mul_f32 v[88:89], v[92:93], v[90:91] op_sel_hi:[0,1]
	v_pk_mul_f32 v[6:7], v[92:93], v[6:7] op_sel_hi:[0,1]
	v_pk_fma_f32 v[90:91], v[102:103], v[6:7], v[42:43]
	v_pk_fma_f32 v[6:7], v[100:101], v[88:89], v[40:41]
	v_cvt_pk_bf16_f32 v4, v4, v5
	v_cvt_pk_bf16_f32 v5, v94, v95
	s_andn2_b64 vcc, exec, s[4:5]
	v_cvt_pk_bf16_f32 v6, v6, v7
	v_cvt_pk_bf16_f32 v7, v90, v91
	ds_write_b128 v144, v[4:7] offset:256
	v_lshl_add_u64 v[150:151], v[10:11], 0, v[148:149]
	s_waitcnt lgkmcnt(0)
	s_barrier
	ds_read_b128 v[168:171], v145
	ds_read_b128 v[172:175], v146
	s_waitcnt lgkmcnt(0)
	s_barrier
	global_store_dwordx4 v[150:151], v[168:171], off offset:-2048 nt
	global_store_dwordx4 v[150:151], v[172:175], off offset:2048 nt
	ds_read_b32 v4, v232 offset:64
	v_lshlrev_b32_e32 v10, 16, v2
	v_lshlrev_b32_e32 v6, 16, v0
	v_and_b32_e32 v7, 0xffff0000, v0
	v_lshlrev_b32_e32 v0, 16, v1
	v_and_b32_e32 v1, 0xffff0000, v1
	v_and_b32_e32 v11, 0xffff0000, v2
	v_lshlrev_b32_e32 v2, 16, v3
	v_and_b32_e32 v3, 0xffff0000, v3
	s_waitcnt lgkmcnt(0)
	v_pk_mul_f32 v[6:7], v[4:5], v[6:7] op_sel_hi:[0,1]
	v_pk_mul_f32 v[0:1], v[4:5], v[0:1] op_sel_hi:[0,1]
	v_pk_fma_f32 v[88:89], v[82:83], v[0:1], v[78:79]
	v_pk_fma_f32 v[0:1], v[80:81], v[6:7], v[76:77]
	v_pk_mul_f32 v[6:7], v[4:5], v[10:11] op_sel_hi:[0,1]
	v_pk_mul_f32 v[2:3], v[4:5], v[2:3] op_sel_hi:[0,1]
	v_pk_fma_f32 v[10:11], v[86:87], v[2:3], v[74:75]
	v_pk_fma_f32 v[2:3], v[84:85], v[6:7], v[72:73]
	v_lshl_add_u64 v[6:7], s[10:11], 0, v[210:211]
	v_cvt_pk_bf16_f32 v0, v0, v1
	v_cvt_pk_bf16_f32 v1, v88, v89
	v_cvt_pk_bf16_f32 v2, v2, v3
	v_cvt_pk_bf16_f32 v3, v10, v11
	v_lshl_add_u64 v[6:7], v[6:7], 0, v[8:9]
	ds_write_b128 v144, v[0:3]
	v_lshlrev_b32_e32 v10, 16, v14
	v_and_b32_e32 v11, 0xffff0000, v14
	v_lshlrev_b32_e32 v0, 16, v12
	v_and_b32_e32 v1, 0xffff0000, v12
	v_lshlrev_b32_e32 v2, 16, v13
	v_and_b32_e32 v3, 0xffff0000, v13
	v_lshlrev_b32_e32 v12, 16, v15
	v_and_b32_e32 v13, 0xffff0000, v15
	v_pk_mul_f32 v[0:1], v[4:5], v[0:1] op_sel_hi:[0,1]
	v_pk_mul_f32 v[2:3], v[4:5], v[2:3] op_sel_hi:[0,1]
	v_pk_mul_f32 v[10:11], v[4:5], v[10:11] op_sel_hi:[0,1]
	v_pk_mul_f32 v[4:5], v[4:5], v[12:13] op_sel_hi:[0,1]
	v_pk_fma_f32 v[2:3], v[98:99], v[2:3], v[66:67]
	v_pk_fma_f32 v[0:1], v[96:97], v[0:1], v[64:65]
	v_pk_fma_f32 v[4:5], v[102:103], v[4:5], v[42:43]
	v_pk_fma_f32 v[10:11], v[100:101], v[10:11], v[40:41]
	v_cvt_pk_bf16_f32 v0, v0, v1
	v_cvt_pk_bf16_f32 v1, v2, v3
	v_lshlrev_b32_e32 v12, 16, v27
	v_cvt_pk_bf16_f32 v2, v10, v11
	v_cvt_pk_bf16_f32 v3, v4, v5
	ds_read_b32 v4, v232 offset:128
	ds_write_b128 v144, v[0:3] offset:256
	v_lshl_add_u64 v[150:151], v[6:7], 0, v[148:149]
	s_waitcnt lgkmcnt(0)
	s_barrier
	ds_read_b128 v[168:171], v145
	ds_read_b128 v[172:175], v146
	s_waitcnt lgkmcnt(0)
	s_barrier
	global_store_dwordx4 v[150:151], v[168:171], off offset:-2048 nt
	global_store_dwordx4 v[150:151], v[172:175], off offset:2048 nt
	v_lshlrev_b32_e32 v6, 16, v18
	v_and_b32_e32 v7, 0xffff0000, v18
	v_lshlrev_b32_e32 v0, 16, v16
	v_and_b32_e32 v1, 0xffff0000, v16
	v_lshlrev_b32_e32 v2, 16, v17
	v_and_b32_e32 v3, 0xffff0000, v17
	s_waitcnt lgkmcnt(0)
	v_pk_mul_f32 v[0:1], v[4:5], v[0:1] op_sel_hi:[0,1]
	v_pk_mul_f32 v[2:3], v[4:5], v[2:3] op_sel_hi:[0,1]
	v_pk_mul_f32 v[6:7], v[4:5], v[6:7] op_sel_hi:[0,1]
	v_lshlrev_b32_e32 v10, 16, v19
	v_and_b32_e32 v11, 0xffff0000, v19
	v_pk_fma_f32 v[2:3], v[82:83], v[2:3], v[78:79]
	v_pk_fma_f32 v[0:1], v[80:81], v[0:1], v[76:77]
	v_pk_fma_f32 v[6:7], v[84:85], v[6:7], v[72:73]
	v_pk_mul_f32 v[10:11], v[4:5], v[10:11] op_sel_hi:[0,1]
	v_cvt_pk_bf16_f32 v0, v0, v1
	v_cvt_pk_bf16_f32 v1, v2, v3
	v_cvt_pk_bf16_f32 v2, v6, v7
	v_lshl_add_u64 v[6:7], s[10:11], 0, v[214:215]
	v_pk_fma_f32 v[10:11], v[86:87], v[10:11], v[74:75]
	v_lshl_add_u64 v[6:7], v[6:7], 0, v[8:9]
	v_cvt_pk_bf16_f32 v3, v10, v11
	ds_write_b128 v144, v[0:3]
	v_lshlrev_b32_e32 v10, 16, v26
	v_and_b32_e32 v11, 0xffff0000, v26
	v_lshlrev_b32_e32 v0, 16, v24
	v_and_b32_e32 v1, 0xffff0000, v24
	v_lshlrev_b32_e32 v2, 16, v25
	v_and_b32_e32 v3, 0xffff0000, v25
	v_and_b32_e32 v13, 0xffff0000, v27
	v_pk_mul_f32 v[0:1], v[4:5], v[0:1] op_sel_hi:[0,1]
	v_pk_mul_f32 v[2:3], v[4:5], v[2:3] op_sel_hi:[0,1]
	v_pk_mul_f32 v[10:11], v[4:5], v[10:11] op_sel_hi:[0,1]
	v_pk_mul_f32 v[4:5], v[4:5], v[12:13] op_sel_hi:[0,1]
	v_pk_fma_f32 v[2:3], v[98:99], v[2:3], v[66:67]
	v_pk_fma_f32 v[0:1], v[96:97], v[0:1], v[64:65]
	v_pk_fma_f32 v[4:5], v[102:103], v[4:5], v[42:43]
	v_pk_fma_f32 v[10:11], v[100:101], v[10:11], v[40:41]
	v_cvt_pk_bf16_f32 v0, v0, v1
	v_cvt_pk_bf16_f32 v1, v2, v3
	v_lshlrev_b32_e32 v12, 16, v31
	v_cvt_pk_bf16_f32 v2, v10, v11
	v_cvt_pk_bf16_f32 v3, v4, v5
	ds_read_b32 v4, v232 offset:192
	ds_write_b128 v144, v[0:3] offset:256
	v_lshl_add_u64 v[150:151], v[6:7], 0, v[148:149]
	s_waitcnt lgkmcnt(0)
	s_barrier
	ds_read_b128 v[168:171], v145
	ds_read_b128 v[172:175], v146
	s_waitcnt lgkmcnt(0)
	s_barrier
	global_store_dwordx4 v[150:151], v[168:171], off offset:-2048 nt
	global_store_dwordx4 v[150:151], v[172:175], off offset:2048 nt
	v_lshlrev_b32_e32 v6, 16, v22
	v_and_b32_e32 v7, 0xffff0000, v22
	v_lshlrev_b32_e32 v0, 16, v20
	v_and_b32_e32 v1, 0xffff0000, v20
	v_lshlrev_b32_e32 v2, 16, v21
	v_and_b32_e32 v3, 0xffff0000, v21
	s_waitcnt lgkmcnt(0)
	v_pk_mul_f32 v[0:1], v[4:5], v[0:1] op_sel_hi:[0,1]
	v_pk_mul_f32 v[2:3], v[4:5], v[2:3] op_sel_hi:[0,1]
	v_pk_mul_f32 v[6:7], v[4:5], v[6:7] op_sel_hi:[0,1]
	v_lshlrev_b32_e32 v10, 16, v23
	v_and_b32_e32 v11, 0xffff0000, v23
	v_pk_fma_f32 v[2:3], v[82:83], v[2:3], v[78:79]
	v_pk_fma_f32 v[0:1], v[80:81], v[0:1], v[76:77]
	v_pk_fma_f32 v[6:7], v[84:85], v[6:7], v[72:73]
	v_pk_mul_f32 v[10:11], v[4:5], v[10:11] op_sel_hi:[0,1]
	v_cvt_pk_bf16_f32 v0, v0, v1
	v_cvt_pk_bf16_f32 v1, v2, v3
	v_cvt_pk_bf16_f32 v2, v6, v7
	v_lshl_add_u64 v[6:7], s[10:11], 0, v[160:161]
	v_pk_fma_f32 v[10:11], v[86:87], v[10:11], v[74:75]
	v_lshl_add_u64 v[6:7], v[6:7], 0, v[8:9]
	v_cvt_pk_bf16_f32 v3, v10, v11
	ds_write_b128 v144, v[0:3]
	v_lshlrev_b32_e32 v10, 16, v30
	v_and_b32_e32 v11, 0xffff0000, v30
	v_lshlrev_b32_e32 v0, 16, v28
	v_and_b32_e32 v1, 0xffff0000, v28
	v_lshlrev_b32_e32 v2, 16, v29
	v_and_b32_e32 v3, 0xffff0000, v29
	v_and_b32_e32 v13, 0xffff0000, v31
	v_pk_mul_f32 v[0:1], v[4:5], v[0:1] op_sel_hi:[0,1]
	v_pk_mul_f32 v[2:3], v[4:5], v[2:3] op_sel_hi:[0,1]
	v_pk_mul_f32 v[10:11], v[4:5], v[10:11] op_sel_hi:[0,1]
	v_pk_mul_f32 v[4:5], v[4:5], v[12:13] op_sel_hi:[0,1]
	v_pk_fma_f32 v[2:3], v[98:99], v[2:3], v[66:67]
	v_pk_fma_f32 v[0:1], v[96:97], v[0:1], v[64:65]
	v_pk_fma_f32 v[4:5], v[102:103], v[4:5], v[42:43]
	v_pk_fma_f32 v[10:11], v[100:101], v[10:11], v[40:41]
	v_cvt_pk_bf16_f32 v0, v0, v1
	v_cvt_pk_bf16_f32 v1, v2, v3
	v_lshlrev_b32_e32 v12, 16, v51
	v_cvt_pk_bf16_f32 v2, v10, v11
	v_cvt_pk_bf16_f32 v3, v4, v5
	ds_read_b32 v4, v232 offset:512
	ds_write_b128 v144, v[0:3] offset:256
	v_lshl_add_u64 v[150:151], v[6:7], 0, v[148:149]
	s_waitcnt lgkmcnt(0)
	s_barrier
	ds_read_b128 v[168:171], v145
	ds_read_b128 v[172:175], v146
	s_waitcnt lgkmcnt(0)
	s_barrier
	global_store_dwordx4 v[150:151], v[168:171], off offset:-2048 nt
	global_store_dwordx4 v[150:151], v[172:175], off offset:2048 nt
	v_lshlrev_b32_e32 v6, 16, v34
	v_and_b32_e32 v7, 0xffff0000, v34
	v_lshlrev_b32_e32 v0, 16, v32
	v_and_b32_e32 v1, 0xffff0000, v32
	v_lshlrev_b32_e32 v2, 16, v33
	v_and_b32_e32 v3, 0xffff0000, v33
	s_waitcnt lgkmcnt(0)
	v_pk_mul_f32 v[0:1], v[4:5], v[0:1] op_sel_hi:[0,1]
	v_pk_mul_f32 v[2:3], v[4:5], v[2:3] op_sel_hi:[0,1]
	v_pk_mul_f32 v[6:7], v[4:5], v[6:7] op_sel_hi:[0,1]
	v_lshlrev_b32_e32 v10, 16, v35
	v_and_b32_e32 v11, 0xffff0000, v35
	v_pk_fma_f32 v[2:3], v[82:83], v[2:3], v[78:79]
	v_pk_fma_f32 v[0:1], v[80:81], v[0:1], v[76:77]
	v_pk_fma_f32 v[6:7], v[84:85], v[6:7], v[72:73]
	v_pk_mul_f32 v[10:11], v[4:5], v[10:11] op_sel_hi:[0,1]
	v_cvt_pk_bf16_f32 v0, v0, v1
	v_cvt_pk_bf16_f32 v1, v2, v3
	v_cvt_pk_bf16_f32 v2, v6, v7
	v_lshl_add_u64 v[6:7], s[10:11], 0, v[162:163]
	v_pk_fma_f32 v[10:11], v[86:87], v[10:11], v[74:75]
	v_lshl_add_u64 v[6:7], v[6:7], 0, v[8:9]
	v_cvt_pk_bf16_f32 v3, v10, v11
	ds_write_b128 v144, v[0:3]
	v_lshlrev_b32_e32 v10, 16, v50
	v_and_b32_e32 v11, 0xffff0000, v50
	v_lshlrev_b32_e32 v0, 16, v48
	v_and_b32_e32 v1, 0xffff0000, v48
	v_lshlrev_b32_e32 v2, 16, v49
	v_and_b32_e32 v3, 0xffff0000, v49
	v_and_b32_e32 v13, 0xffff0000, v51
	v_pk_mul_f32 v[0:1], v[4:5], v[0:1] op_sel_hi:[0,1]
	v_pk_mul_f32 v[2:3], v[4:5], v[2:3] op_sel_hi:[0,1]
	v_pk_mul_f32 v[10:11], v[4:5], v[10:11] op_sel_hi:[0,1]
	v_pk_mul_f32 v[4:5], v[4:5], v[12:13] op_sel_hi:[0,1]
	v_pk_fma_f32 v[2:3], v[98:99], v[2:3], v[66:67]
	v_pk_fma_f32 v[0:1], v[96:97], v[0:1], v[64:65]
	v_pk_fma_f32 v[4:5], v[102:103], v[4:5], v[42:43]
	v_pk_fma_f32 v[10:11], v[100:101], v[10:11], v[40:41]
	v_cvt_pk_bf16_f32 v0, v0, v1
	v_cvt_pk_bf16_f32 v1, v2, v3
	v_lshlrev_b32_e32 v12, 16, v55
	v_cvt_pk_bf16_f32 v2, v10, v11
	v_cvt_pk_bf16_f32 v3, v4, v5
	ds_read_b32 v4, v232 offset:576
	ds_write_b128 v144, v[0:3] offset:256
	v_lshl_add_u64 v[150:151], v[6:7], 0, v[148:149]
	s_waitcnt lgkmcnt(0)
	s_barrier
	ds_read_b128 v[168:171], v145
	ds_read_b128 v[172:175], v146
	s_waitcnt lgkmcnt(0)
	s_barrier
	global_store_dwordx4 v[150:151], v[168:171], off offset:-2048 nt
	global_store_dwordx4 v[150:151], v[172:175], off offset:2048 nt
	v_lshlrev_b32_e32 v6, 16, v46
	v_and_b32_e32 v7, 0xffff0000, v46
	v_lshlrev_b32_e32 v0, 16, v44
	v_and_b32_e32 v1, 0xffff0000, v44
	v_lshlrev_b32_e32 v2, 16, v45
	v_and_b32_e32 v3, 0xffff0000, v45
	s_waitcnt lgkmcnt(0)
	v_pk_mul_f32 v[0:1], v[4:5], v[0:1] op_sel_hi:[0,1]
	v_pk_mul_f32 v[2:3], v[4:5], v[2:3] op_sel_hi:[0,1]
	v_pk_mul_f32 v[6:7], v[4:5], v[6:7] op_sel_hi:[0,1]
	v_lshlrev_b32_e32 v10, 16, v47
	v_and_b32_e32 v11, 0xffff0000, v47
	v_pk_fma_f32 v[2:3], v[82:83], v[2:3], v[78:79]
	v_pk_fma_f32 v[0:1], v[80:81], v[0:1], v[76:77]
	v_pk_fma_f32 v[6:7], v[84:85], v[6:7], v[72:73]
	v_pk_mul_f32 v[10:11], v[4:5], v[10:11] op_sel_hi:[0,1]
	v_cvt_pk_bf16_f32 v0, v0, v1
	v_cvt_pk_bf16_f32 v1, v2, v3
	v_cvt_pk_bf16_f32 v2, v6, v7
	v_lshl_add_u64 v[6:7], s[10:11], 0, v[164:165]
	v_pk_fma_f32 v[10:11], v[86:87], v[10:11], v[74:75]
	v_lshl_add_u64 v[6:7], v[6:7], 0, v[8:9]
	v_cvt_pk_bf16_f32 v3, v10, v11
	ds_write_b128 v144, v[0:3]
	v_lshlrev_b32_e32 v10, 16, v54
	v_and_b32_e32 v11, 0xffff0000, v54
	v_lshlrev_b32_e32 v0, 16, v52
	v_and_b32_e32 v1, 0xffff0000, v52
	v_lshlrev_b32_e32 v2, 16, v53
	v_and_b32_e32 v3, 0xffff0000, v53
	v_and_b32_e32 v13, 0xffff0000, v55
	v_pk_mul_f32 v[0:1], v[4:5], v[0:1] op_sel_hi:[0,1]
	v_pk_mul_f32 v[2:3], v[4:5], v[2:3] op_sel_hi:[0,1]
	v_pk_mul_f32 v[10:11], v[4:5], v[10:11] op_sel_hi:[0,1]
	v_pk_mul_f32 v[4:5], v[4:5], v[12:13] op_sel_hi:[0,1]
	v_pk_fma_f32 v[2:3], v[98:99], v[2:3], v[66:67]
	v_pk_fma_f32 v[0:1], v[96:97], v[0:1], v[64:65]
	v_pk_fma_f32 v[4:5], v[102:103], v[4:5], v[42:43]
	v_pk_fma_f32 v[10:11], v[100:101], v[10:11], v[40:41]
	v_cvt_pk_bf16_f32 v0, v0, v1
	v_cvt_pk_bf16_f32 v1, v2, v3
	v_lshlrev_b32_e32 v12, 16, v71
	v_cvt_pk_bf16_f32 v2, v10, v11
	v_cvt_pk_bf16_f32 v3, v4, v5
	ds_read_b32 v4, v232 offset:640
	ds_write_b128 v144, v[0:3] offset:256
	v_lshl_add_u64 v[150:151], v[6:7], 0, v[148:149]
	s_waitcnt lgkmcnt(0)
	s_barrier
	ds_read_b128 v[168:171], v145
	ds_read_b128 v[172:175], v146
	s_waitcnt lgkmcnt(0)
	s_barrier
	global_store_dwordx4 v[150:151], v[168:171], off offset:-2048 nt
	global_store_dwordx4 v[150:151], v[172:175], off offset:2048 nt
	v_lshlrev_b32_e32 v6, 16, v58
	v_and_b32_e32 v7, 0xffff0000, v58
	v_lshlrev_b32_e32 v0, 16, v56
	v_and_b32_e32 v1, 0xffff0000, v56
	v_lshlrev_b32_e32 v2, 16, v57
	v_and_b32_e32 v3, 0xffff0000, v57
	s_waitcnt lgkmcnt(0)
	v_pk_mul_f32 v[0:1], v[4:5], v[0:1] op_sel_hi:[0,1]
	v_pk_mul_f32 v[2:3], v[4:5], v[2:3] op_sel_hi:[0,1]
	v_pk_mul_f32 v[6:7], v[4:5], v[6:7] op_sel_hi:[0,1]
	v_lshlrev_b32_e32 v10, 16, v59
	v_and_b32_e32 v11, 0xffff0000, v59
	v_pk_fma_f32 v[2:3], v[82:83], v[2:3], v[78:79]
	v_pk_fma_f32 v[0:1], v[80:81], v[0:1], v[76:77]
	v_pk_fma_f32 v[6:7], v[84:85], v[6:7], v[72:73]
	v_pk_mul_f32 v[10:11], v[4:5], v[10:11] op_sel_hi:[0,1]
	v_cvt_pk_bf16_f32 v0, v0, v1
	v_cvt_pk_bf16_f32 v1, v2, v3
	v_cvt_pk_bf16_f32 v2, v6, v7
	v_lshl_add_u64 v[6:7], s[10:11], 0, v[120:121]
	v_pk_fma_f32 v[10:11], v[86:87], v[10:11], v[74:75]
	v_lshl_add_u64 v[6:7], v[6:7], 0, v[8:9]
	v_cvt_pk_bf16_f32 v3, v10, v11
	ds_write_b128 v144, v[0:3]
	v_lshlrev_b32_e32 v10, 16, v70
	v_and_b32_e32 v11, 0xffff0000, v70
	v_lshlrev_b32_e32 v0, 16, v68
	v_and_b32_e32 v1, 0xffff0000, v68
	v_lshlrev_b32_e32 v2, 16, v69
	v_and_b32_e32 v3, 0xffff0000, v69
	v_and_b32_e32 v13, 0xffff0000, v71
	v_pk_mul_f32 v[0:1], v[4:5], v[0:1] op_sel_hi:[0,1]
	v_pk_mul_f32 v[2:3], v[4:5], v[2:3] op_sel_hi:[0,1]
	v_pk_mul_f32 v[10:11], v[4:5], v[10:11] op_sel_hi:[0,1]
	v_pk_mul_f32 v[4:5], v[4:5], v[12:13] op_sel_hi:[0,1]
	v_pk_fma_f32 v[2:3], v[98:99], v[2:3], v[66:67]
	v_pk_fma_f32 v[0:1], v[96:97], v[0:1], v[64:65]
	v_pk_fma_f32 v[4:5], v[102:103], v[4:5], v[42:43]
	v_pk_fma_f32 v[10:11], v[100:101], v[10:11], v[40:41]
	v_cvt_pk_bf16_f32 v0, v0, v1
	v_cvt_pk_bf16_f32 v1, v2, v3
	s_mov_b64 s[4:5], -1
	v_cvt_pk_bf16_f32 v2, v10, v11
	v_cvt_pk_bf16_f32 v3, v4, v5
	ds_read_b32 v4, v232 offset:704
	ds_write_b128 v144, v[0:3] offset:256
	v_lshl_add_u64 v[150:151], v[6:7], 0, v[148:149]
	s_waitcnt lgkmcnt(0)
	s_barrier
	ds_read_b128 v[168:171], v145
	ds_read_b128 v[172:175], v146
	s_waitcnt lgkmcnt(0)
	s_barrier
	global_store_dwordx4 v[150:151], v[168:171], off offset:-2048 nt
	global_store_dwordx4 v[150:151], v[172:175], off offset:2048 nt
	v_lshlrev_b32_e32 v6, 16, v62
	v_and_b32_e32 v7, 0xffff0000, v62
	v_lshlrev_b32_e32 v0, 16, v60
	v_and_b32_e32 v1, 0xffff0000, v60
	v_lshlrev_b32_e32 v2, 16, v61
	v_and_b32_e32 v3, 0xffff0000, v61
	s_waitcnt lgkmcnt(0)
	v_pk_mul_f32 v[0:1], v[4:5], v[0:1] op_sel_hi:[0,1]
	v_pk_mul_f32 v[2:3], v[4:5], v[2:3] op_sel_hi:[0,1]
	v_pk_mul_f32 v[6:7], v[4:5], v[6:7] op_sel_hi:[0,1]
	v_lshlrev_b32_e32 v10, 16, v63
	v_and_b32_e32 v11, 0xffff0000, v63
	v_pk_fma_f32 v[2:3], v[82:83], v[2:3], v[78:79]
	v_pk_fma_f32 v[0:1], v[80:81], v[0:1], v[76:77]
	v_pk_fma_f32 v[6:7], v[84:85], v[6:7], v[72:73]
	v_pk_mul_f32 v[10:11], v[4:5], v[10:11] op_sel_hi:[0,1]
	v_cvt_pk_bf16_f32 v0, v0, v1
	v_cvt_pk_bf16_f32 v1, v2, v3
	v_cvt_pk_bf16_f32 v2, v6, v7
	v_lshl_add_u64 v[6:7], s[10:11], 0, v[122:123]
	v_pk_fma_f32 v[10:11], v[86:87], v[10:11], v[74:75]
	v_lshl_add_u64 v[6:7], v[6:7], 0, v[8:9]
	v_cvt_pk_bf16_f32 v3, v10, v11
	ds_write_b128 v144, v[0:3]
	v_lshlrev_b32_e32 v8, 16, v38
	v_and_b32_e32 v9, 0xffff0000, v38
	v_lshlrev_b32_e32 v0, 16, v36
	v_and_b32_e32 v1, 0xffff0000, v36
	v_lshlrev_b32_e32 v2, 16, v37
	v_and_b32_e32 v3, 0xffff0000, v37
	v_lshlrev_b32_e32 v10, 16, v39
	v_and_b32_e32 v11, 0xffff0000, v39
	v_pk_mul_f32 v[0:1], v[4:5], v[0:1] op_sel_hi:[0,1]
	v_pk_mul_f32 v[2:3], v[4:5], v[2:3] op_sel_hi:[0,1]
	v_pk_fma_f32 v[2:3], v[98:99], v[2:3], v[66:67]
	v_pk_fma_f32 v[0:1], v[96:97], v[0:1], v[64:65]
	v_pk_mul_f32 v[8:9], v[4:5], v[8:9] op_sel_hi:[0,1]
	v_pk_mul_f32 v[4:5], v[4:5], v[10:11] op_sel_hi:[0,1]
	v_pk_fma_f32 v[4:5], v[102:103], v[4:5], v[42:43]
	v_pk_fma_f32 v[8:9], v[100:101], v[8:9], v[40:41]
	v_cvt_pk_bf16_f32 v0, v0, v1
	v_cvt_pk_bf16_f32 v1, v2, v3
	s_nop 0
	v_cvt_pk_bf16_f32 v2, v8, v9
	v_cvt_pk_bf16_f32 v3, v4, v5
	ds_write_b128 v144, v[0:3] offset:256
	v_lshl_add_u64 v[150:151], v[6:7], 0, v[148:149]
	s_waitcnt lgkmcnt(0)
	s_barrier
	ds_read_b128 v[168:171], v145
	ds_read_b128 v[172:175], v146
	s_waitcnt lgkmcnt(0)
	s_barrier
	global_store_dwordx4 v[150:151], v[168:171], off offset:-2048 nt
	global_store_dwordx4 v[150:151], v[172:175], off offset:2048 nt
	s_cbranch_vccnz .LBB0_1471
	s_andn2_b64 vcc, exec, s[8:9]
	s_cbranch_vccnz .LBB0_1470
	s_barrier
	s_branch .LBB0_1470
